# grid barrier: XCD leaders also invalidate early (after their TOP arrival) on top of the broadcast release
# speedup vs baseline: 1.0053x; 1.0017x over previous
; __device__ __forceinline__ unsigned xb_ld(unsigned* p)              { return __hip_atomic_load(p, __ATOMIC_RELAXED, __HIP_MEMORY_SCOPE_AGENT); }
; __device__ __forceinline__ unsigned xb_add(unsigned* p, unsigned v) { return __hip_atomic_fetch_add(p, v, __ATOMIC_RELAXED, __HIP_MEMORY_SCOPE_AGENT); }
; #define XB_SPIN(cond, bar) do { unsigned _sp = 0; while (cond) { __builtin_amdgcn_s_sleep(1); \
;     if ((++_sp & 255u) == 0u) { if (xb_ld(&(bar)[XB_TMO])) break; if (_sp > XB_SPIN_CAP) { atomicAdd(&(bar)[XB_TMO], 1u); break; } } } } while (0)
; template <bool FLUSH> __device__ __forceinline__ void xcd_barrier(const XcdBarrier& b) {
;     ...
;             __builtin_amdgcn_fence(__ATOMIC_ACQUIRE, "agent");
;             xb_add(&bar[XB_XGEN(b.x)], 1u);
;             asm volatile("s_waitcnt vmcnt(0)" ::: "memory");
;         } else {
;             XB_SPIN(xb_ld(&bar[XB_XGEN(b.x)]) == gen, bar);
;             __builtin_amdgcn_fence(__ATOMIC_ACQUIRE, "agent");
;             asm volatile("s_waitcnt vmcnt(0)" ::: "memory");
;         }
;     }
;     __syncthreads();
.LBB0_115:
	s_or_b64 exec, exec, s[6:7]
	v_mov_b32_e32 v0, 0x2000
	v_mov_b32_e32 v1, 1
	s_waitcnt vmcnt(0)
.LBB0_116:
	s_or_b64 exec, exec, s[2:3]
	s_waitcnt lgkmcnt(0)
	s_barrier

; __device__ __forceinline__ unsigned xb_ld(unsigned* p)              { return __hip_atomic_load(p, __ATOMIC_RELAXED, __HIP_MEMORY_SCOPE_AGENT); }
; __device__ __forceinline__ unsigned xb_add(unsigned* p, unsigned v) { return __hip_atomic_fetch_add(p, v, __ATOMIC_RELAXED, __HIP_MEMORY_SCOPE_AGENT); }
; #define XB_SPIN(cond, bar) do { unsigned _sp = 0; while (cond) { __builtin_amdgcn_s_sleep(1); \
;     if ((++_sp & 255u) == 0u) { if (xb_ld(&(bar)[XB_TMO])) break; if (_sp > XB_SPIN_CAP) { atomicAdd(&(bar)[XB_TMO], 1u); break; } } } } while (0)
; template <bool FLUSH> __device__ __forceinline__ void xcd_barrier(const XcdBarrier& b) {
;     ...
;             __builtin_amdgcn_fence(__ATOMIC_ACQUIRE, "agent");
;             xb_add(&bar[XB_XGEN(b.x)], 1u);
;             asm volatile("s_waitcnt vmcnt(0)" ::: "memory");
;         } else {
;             XB_SPIN(xb_ld(&bar[XB_XGEN(b.x)]) == gen, bar);
;             __builtin_amdgcn_fence(__ATOMIC_ACQUIRE, "agent");
;             asm volatile("s_waitcnt vmcnt(0)" ::: "memory");
;         }
;     }
;     __syncthreads();
.LBB0_270:
	s_or_b64 exec, exec, s[6:7]
	v_mov_b32_e32 v0, 0x2000
	v_mov_b32_e32 v1, 1
	s_waitcnt vmcnt(0)
.LBB0_271:
	s_or_b64 exec, exec, s[2:3]
	s_waitcnt lgkmcnt(0)
	s_barrier

; __device__ __forceinline__ unsigned xb_ld(unsigned* p)              { return __hip_atomic_load(p, __ATOMIC_RELAXED, __HIP_MEMORY_SCOPE_AGENT); }
; __device__ __forceinline__ unsigned xb_add(unsigned* p, unsigned v) { return __hip_atomic_fetch_add(p, v, __ATOMIC_RELAXED, __HIP_MEMORY_SCOPE_AGENT); }
; #define XB_SPIN(cond, bar) do { unsigned _sp = 0; while (cond) { __builtin_amdgcn_s_sleep(1); \
;     if ((++_sp & 255u) == 0u) { if (xb_ld(&(bar)[XB_TMO])) break; if (_sp > XB_SPIN_CAP) { atomicAdd(&(bar)[XB_TMO], 1u); break; } } } } while (0)
; template <bool FLUSH> __device__ __forceinline__ void xcd_barrier(const XcdBarrier& b) {
;     ...
;             __builtin_amdgcn_fence(__ATOMIC_ACQUIRE, "agent");
;             xb_add(&bar[XB_XGEN(b.x)], 1u);
;             asm volatile("s_waitcnt vmcnt(0)" ::: "memory");
;         } else {
;             XB_SPIN(xb_ld(&bar[XB_XGEN(b.x)]) == gen, bar);
;             __builtin_amdgcn_fence(__ATOMIC_ACQUIRE, "agent");
;             asm volatile("s_waitcnt vmcnt(0)" ::: "memory");
;         }
;     }
;     __syncthreads();
.LBB0_362:
	s_or_b64 exec, exec, s[6:7]
	v_mov_b32_e32 v0, 0x2000
	v_mov_b32_e32 v1, 1
	s_waitcnt vmcnt(0)
.LBB0_363:
	s_or_b64 exec, exec, s[2:3]
	s_waitcnt lgkmcnt(0)
	s_barrier

; __device__ __forceinline__ unsigned xb_ld(unsigned* p)              { return __hip_atomic_load(p, __ATOMIC_RELAXED, __HIP_MEMORY_SCOPE_AGENT); }
; __device__ __forceinline__ unsigned xb_add(unsigned* p, unsigned v) { return __hip_atomic_fetch_add(p, v, __ATOMIC_RELAXED, __HIP_MEMORY_SCOPE_AGENT); }
; #define XB_SPIN(cond, bar) do { unsigned _sp = 0; while (cond) { __builtin_amdgcn_s_sleep(1); \
;     if ((++_sp & 255u) == 0u) { if (xb_ld(&(bar)[XB_TMO])) break; if (_sp > XB_SPIN_CAP) { atomicAdd(&(bar)[XB_TMO], 1u); break; } } } } while (0)
; template <bool FLUSH> __device__ __forceinline__ void xcd_barrier(const XcdBarrier& b) {
;     ...
;             __builtin_amdgcn_fence(__ATOMIC_ACQUIRE, "agent");
;             xb_add(&bar[XB_XGEN(b.x)], 1u);
;             asm volatile("s_waitcnt vmcnt(0)" ::: "memory");
;         } else {
;             XB_SPIN(xb_ld(&bar[XB_XGEN(b.x)]) == gen, bar);
;             __builtin_amdgcn_fence(__ATOMIC_ACQUIRE, "agent");
;             asm volatile("s_waitcnt vmcnt(0)" ::: "memory");
;         }
;     }
;     __syncthreads();
.LBB0_473:
	s_or_b64 exec, exec, s[6:7]
	v_mov_b32_e32 v0, 0x2000
	v_mov_b32_e32 v1, 1
	s_waitcnt vmcnt(0)
.LBB0_474:
	s_or_b64 exec, exec, s[2:3]
	s_waitcnt lgkmcnt(0)
	s_barrier

; __device__ __forceinline__ unsigned xb_ld(unsigned* p)              { return __hip_atomic_load(p, __ATOMIC_RELAXED, __HIP_MEMORY_SCOPE_AGENT); }
; __device__ __forceinline__ unsigned xb_add(unsigned* p, unsigned v) { return __hip_atomic_fetch_add(p, v, __ATOMIC_RELAXED, __HIP_MEMORY_SCOPE_AGENT); }
; #define XB_SPIN(cond, bar) do { unsigned _sp = 0; while (cond) { __builtin_amdgcn_s_sleep(1); \
;     if ((++_sp & 255u) == 0u) { if (xb_ld(&(bar)[XB_TMO])) break; if (_sp > XB_SPIN_CAP) { atomicAdd(&(bar)[XB_TMO], 1u); break; } } } } while (0)
; template <bool FLUSH> __device__ __forceinline__ void xcd_barrier(const XcdBarrier& b) {
;     ...
;             __builtin_amdgcn_fence(__ATOMIC_ACQUIRE, "agent");
;             xb_add(&bar[XB_XGEN(b.x)], 1u);
;             asm volatile("s_waitcnt vmcnt(0)" ::: "memory");
;         } else {
;             XB_SPIN(xb_ld(&bar[XB_XGEN(b.x)]) == gen, bar);
;             __builtin_amdgcn_fence(__ATOMIC_ACQUIRE, "agent");
;             asm volatile("s_waitcnt vmcnt(0)" ::: "memory");
;         }
;     }
;     __syncthreads();
.LBB0_616:
	s_or_b64 exec, exec, s[6:7]
	v_mov_b32_e32 v0, 0x2000
	v_mov_b32_e32 v1, 1
	s_waitcnt vmcnt(0)
.LBB0_617:
	s_or_b64 exec, exec, s[2:3]
	s_waitcnt lgkmcnt(0)
	s_barrier

; __device__ __forceinline__ unsigned xb_ld(unsigned* p)              { return __hip_atomic_load(p, __ATOMIC_RELAXED, __HIP_MEMORY_SCOPE_AGENT); }
; __device__ __forceinline__ unsigned xb_add(unsigned* p, unsigned v) { return __hip_atomic_fetch_add(p, v, __ATOMIC_RELAXED, __HIP_MEMORY_SCOPE_AGENT); }
; #define XB_SPIN(cond, bar) do { unsigned _sp = 0; while (cond) { __builtin_amdgcn_s_sleep(1); \
;     if ((++_sp & 255u) == 0u) { if (xb_ld(&(bar)[XB_TMO])) break; if (_sp > XB_SPIN_CAP) { atomicAdd(&(bar)[XB_TMO], 1u); break; } } } } while (0)
; template <bool FLUSH> __device__ __forceinline__ void xcd_barrier(const XcdBarrier& b) {
;     ...
;             __builtin_amdgcn_fence(__ATOMIC_ACQUIRE, "agent");
;             xb_add(&bar[XB_XGEN(b.x)], 1u);
;             asm volatile("s_waitcnt vmcnt(0)" ::: "memory");
;         } else {
;             XB_SPIN(xb_ld(&bar[XB_XGEN(b.x)]) == gen, bar);
;             __builtin_amdgcn_fence(__ATOMIC_ACQUIRE, "agent");
;             asm volatile("s_waitcnt vmcnt(0)" ::: "memory");
;         }
;     }
;     __syncthreads();
.LBB0_737:
	s_or_b64 exec, exec, s[6:7]
	v_mov_b32_e32 v0, 0x2000
	v_mov_b32_e32 v1, 1
	s_waitcnt vmcnt(0)
.LBB0_738:
	s_or_b64 exec, exec, s[2:3]
	s_waitcnt lgkmcnt(0)
	s_barrier

; __device__ __forceinline__ unsigned xb_ld(unsigned* p)              { return __hip_atomic_load(p, __ATOMIC_RELAXED, __HIP_MEMORY_SCOPE_AGENT); }
; __device__ __forceinline__ unsigned xb_add(unsigned* p, unsigned v) { return __hip_atomic_fetch_add(p, v, __ATOMIC_RELAXED, __HIP_MEMORY_SCOPE_AGENT); }
; #define XB_SPIN(cond, bar) do { unsigned _sp = 0; while (cond) { __builtin_amdgcn_s_sleep(1); \
;     if ((++_sp & 255u) == 0u) { if (xb_ld(&(bar)[XB_TMO])) break; if (_sp > XB_SPIN_CAP) { atomicAdd(&(bar)[XB_TMO], 1u); break; } } } } while (0)
; template <bool FLUSH> __device__ __forceinline__ void xcd_barrier(const XcdBarrier& b) {
;     ...
;             __builtin_amdgcn_fence(__ATOMIC_ACQUIRE, "agent");
;             xb_add(&bar[XB_XGEN(b.x)], 1u);
;             asm volatile("s_waitcnt vmcnt(0)" ::: "memory");
;         } else {
;             XB_SPIN(xb_ld(&bar[XB_XGEN(b.x)]) == gen, bar);
;             __builtin_amdgcn_fence(__ATOMIC_ACQUIRE, "agent");
;             asm volatile("s_waitcnt vmcnt(0)" ::: "memory");
;         }
;     }
;     __syncthreads();
.LBB0_951:
	s_or_b64 exec, exec, s[6:7]
	v_mov_b32_e32 v0, 0x2000
	v_mov_b32_e32 v1, 1
	s_waitcnt vmcnt(0)
.LBB0_952:
	s_or_b64 exec, exec, s[2:3]
	s_waitcnt lgkmcnt(0)
	s_barrier

; __device__ __forceinline__ unsigned xb_ld(unsigned* p)              { return __hip_atomic_load(p, __ATOMIC_RELAXED, __HIP_MEMORY_SCOPE_AGENT); }
; __device__ __forceinline__ unsigned xb_add(unsigned* p, unsigned v) { return __hip_atomic_fetch_add(p, v, __ATOMIC_RELAXED, __HIP_MEMORY_SCOPE_AGENT); }
; #define XB_SPIN(cond, bar) do { unsigned _sp = 0; while (cond) { __builtin_amdgcn_s_sleep(1); \
;     if ((++_sp & 255u) == 0u) { if (xb_ld(&(bar)[XB_TMO])) break; if (_sp > XB_SPIN_CAP) { atomicAdd(&(bar)[XB_TMO], 1u); break; } } } } while (0)
; template <bool FLUSH> __device__ __forceinline__ void xcd_barrier(const XcdBarrier& b) {
;     ...
;             __builtin_amdgcn_fence(__ATOMIC_ACQUIRE, "agent");
;             xb_add(&bar[XB_XGEN(b.x)], 1u);
;             asm volatile("s_waitcnt vmcnt(0)" ::: "memory");
;         } else {
;             XB_SPIN(xb_ld(&bar[XB_XGEN(b.x)]) == gen, bar);
;             __builtin_amdgcn_fence(__ATOMIC_ACQUIRE, "agent");
;             asm volatile("s_waitcnt vmcnt(0)" ::: "memory");
;         }
;     }
;     __syncthreads();
.LBB0_1062:
	s_or_b64 exec, exec, s[6:7]
	v_mov_b32_e32 v0, 0x2000
	v_mov_b32_e32 v1, 1
	s_waitcnt vmcnt(0)
.LBB0_1063:
	s_or_b64 exec, exec, s[2:3]
	s_waitcnt lgkmcnt(0)
	s_barrier

; __device__ __forceinline__ unsigned xb_ld(unsigned* p)              { return __hip_atomic_load(p, __ATOMIC_RELAXED, __HIP_MEMORY_SCOPE_AGENT); }
; __device__ __forceinline__ unsigned xb_add(unsigned* p, unsigned v) { return __hip_atomic_fetch_add(p, v, __ATOMIC_RELAXED, __HIP_MEMORY_SCOPE_AGENT); }
; #define XB_SPIN(cond, bar) do { unsigned _sp = 0; while (cond) { __builtin_amdgcn_s_sleep(1); \
;     if ((++_sp & 255u) == 0u) { if (xb_ld(&(bar)[XB_TMO])) break; if (_sp > XB_SPIN_CAP) { atomicAdd(&(bar)[XB_TMO], 1u); break; } } } } while (0)
; template <bool FLUSH> __device__ __forceinline__ void xcd_barrier(const XcdBarrier& b) {
;     ...
;             __builtin_amdgcn_fence(__ATOMIC_ACQUIRE, "agent");
;             xb_add(&bar[XB_XGEN(b.x)], 1u);
;             asm volatile("s_waitcnt vmcnt(0)" ::: "memory");
;         } else {
;             XB_SPIN(xb_ld(&bar[XB_XGEN(b.x)]) == gen, bar);
;             __builtin_amdgcn_fence(__ATOMIC_ACQUIRE, "agent");
;             asm volatile("s_waitcnt vmcnt(0)" ::: "memory");
;         }
;     }
;     __syncthreads();
.LBB0_1154:
	s_or_b64 exec, exec, s[6:7]
	v_mov_b32_e32 v0, 0x2000
	v_mov_b32_e32 v1, 1
	s_waitcnt vmcnt(0)
.LBB0_1155:
	s_or_b64 exec, exec, s[2:3]
	s_waitcnt lgkmcnt(0)
	s_barrier

; __device__ __forceinline__ unsigned xb_ld(unsigned* p)              { return __hip_atomic_load(p, __ATOMIC_RELAXED, __HIP_MEMORY_SCOPE_AGENT); }
; __device__ __forceinline__ unsigned xb_add(unsigned* p, unsigned v) { return __hip_atomic_fetch_add(p, v, __ATOMIC_RELAXED, __HIP_MEMORY_SCOPE_AGENT); }
; #define XB_SPIN(cond, bar) do { unsigned _sp = 0; while (cond) { __builtin_amdgcn_s_sleep(1); \
;     if ((++_sp & 255u) == 0u) { if (xb_ld(&(bar)[XB_TMO])) break; if (_sp > XB_SPIN_CAP) { atomicAdd(&(bar)[XB_TMO], 1u); break; } } } } while (0)
; template <bool FLUSH> __device__ __forceinline__ void xcd_barrier(const XcdBarrier& b) {
;     ...
;             __builtin_amdgcn_fence(__ATOMIC_ACQUIRE, "agent");
;             xb_add(&bar[XB_XGEN(b.x)], 1u);
;             asm volatile("s_waitcnt vmcnt(0)" ::: "memory");
;         } else {
;             XB_SPIN(xb_ld(&bar[XB_XGEN(b.x)]) == gen, bar);
;             __builtin_amdgcn_fence(__ATOMIC_ACQUIRE, "agent");
;             asm volatile("s_waitcnt vmcnt(0)" ::: "memory");
;         }
;     }
;     __syncthreads();
.LBB0_1305:
	s_or_b64 exec, exec, s[6:7]
	v_mov_b32_e32 v0, 0x2000
	v_mov_b32_e32 v1, 1
	s_waitcnt vmcnt(0)
.LBB0_1306:
	s_or_b64 exec, exec, s[2:3]
	s_waitcnt lgkmcnt(0)
	s_barrier

; __device__ __forceinline__ unsigned xb_ld(unsigned* p)              { return __hip_atomic_load(p, __ATOMIC_RELAXED, __HIP_MEMORY_SCOPE_AGENT); }
; __device__ __forceinline__ unsigned xb_add(unsigned* p, unsigned v) { return __hip_atomic_fetch_add(p, v, __ATOMIC_RELAXED, __HIP_MEMORY_SCOPE_AGENT); }
; #define XB_SPIN(cond, bar) do { unsigned _sp = 0; while (cond) { __builtin_amdgcn_s_sleep(1); \
;     if ((++_sp & 255u) == 0u) { if (xb_ld(&(bar)[XB_TMO])) break; if (_sp > XB_SPIN_CAP) { atomicAdd(&(bar)[XB_TMO], 1u); break; } } } } while (0)
; template <bool FLUSH> __device__ __forceinline__ void xcd_barrier(const XcdBarrier& b) {
;     ...
;             __builtin_amdgcn_fence(__ATOMIC_ACQUIRE, "agent");
;             xb_add(&bar[XB_XGEN(b.x)], 1u);
;             asm volatile("s_waitcnt vmcnt(0)" ::: "memory");
;         } else {
;             XB_SPIN(xb_ld(&bar[XB_XGEN(b.x)]) == gen, bar);
;             __builtin_amdgcn_fence(__ATOMIC_ACQUIRE, "agent");
;             asm volatile("s_waitcnt vmcnt(0)" ::: "memory");
;         }
;     }
;     __syncthreads();
.LBB0_1397:
	s_or_b64 exec, exec, s[6:7]
	v_mov_b32_e32 v0, 0x2000
	v_mov_b32_e32 v1, 1
	s_waitcnt vmcnt(0)
.LBB0_1398:
	s_or_b64 exec, exec, s[2:3]
	s_waitcnt lgkmcnt(0)
	s_barrier

; __device__ __forceinline__ unsigned xb_ld(unsigned* p)              { return __hip_atomic_load(p, __ATOMIC_RELAXED, __HIP_MEMORY_SCOPE_AGENT); }
; __device__ __forceinline__ unsigned xb_add(unsigned* p, unsigned v) { return __hip_atomic_fetch_add(p, v, __ATOMIC_RELAXED, __HIP_MEMORY_SCOPE_AGENT); }
; #define XB_SPIN(cond, bar) do { unsigned _sp = 0; while (cond) { __builtin_amdgcn_s_sleep(1); \
;     if ((++_sp & 255u) == 0u) { if (xb_ld(&(bar)[XB_TMO])) break; if (_sp > XB_SPIN_CAP) { atomicAdd(&(bar)[XB_TMO], 1u); break; } } } } while (0)
; template <bool FLUSH> __device__ __forceinline__ void xcd_barrier(const XcdBarrier& b) {
;     ...
;             __builtin_amdgcn_fence(__ATOMIC_ACQUIRE, "agent");
;             xb_add(&bar[XB_XGEN(b.x)], 1u);
;             asm volatile("s_waitcnt vmcnt(0)" ::: "memory");
;         } else {
;             XB_SPIN(xb_ld(&bar[XB_XGEN(b.x)]) == gen, bar);
;             __builtin_amdgcn_fence(__ATOMIC_ACQUIRE, "agent");
;             asm volatile("s_waitcnt vmcnt(0)" ::: "memory");
;         }
;     }
;     __syncthreads();
.LBB0_1508:
	s_or_b64 exec, exec, s[6:7]
	v_mov_b32_e32 v0, 0x2000
	v_mov_b32_e32 v1, 1
	s_waitcnt vmcnt(0)
.LBB0_1509:
	s_or_b64 exec, exec, s[2:3]
	s_waitcnt lgkmcnt(0)
	s_barrier

; __device__ __forceinline__ unsigned xb_ld(unsigned* p)              { return __hip_atomic_load(p, __ATOMIC_RELAXED, __HIP_MEMORY_SCOPE_AGENT); }
; __device__ __forceinline__ unsigned xb_add(unsigned* p, unsigned v) { return __hip_atomic_fetch_add(p, v, __ATOMIC_RELAXED, __HIP_MEMORY_SCOPE_AGENT); }
; #define XB_SPIN(cond, bar) do { unsigned _sp = 0; while (cond) { __builtin_amdgcn_s_sleep(1); \
;     if ((++_sp & 255u) == 0u) { if (xb_ld(&(bar)[XB_TMO])) break; if (_sp > XB_SPIN_CAP) { atomicAdd(&(bar)[XB_TMO], 1u); break; } } } } while (0)
; template <bool FLUSH> __device__ __forceinline__ void xcd_barrier(const XcdBarrier& b) {
;     ...
;             __builtin_amdgcn_fence(__ATOMIC_ACQUIRE, "agent");
;             xb_add(&bar[XB_XGEN(b.x)], 1u);
;             asm volatile("s_waitcnt vmcnt(0)" ::: "memory");
;         } else {
;             XB_SPIN(xb_ld(&bar[XB_XGEN(b.x)]) == gen, bar);
;             __builtin_amdgcn_fence(__ATOMIC_ACQUIRE, "agent");
;             asm volatile("s_waitcnt vmcnt(0)" ::: "memory");
;         }
;     }
;     __syncthreads();
.LBB0_1651:
	s_or_b64 exec, exec, s[6:7]
	v_mov_b32_e32 v0, 0x2000
	v_mov_b32_e32 v1, 1
	s_waitcnt vmcnt(0)
.LBB0_1652:
	s_or_b64 exec, exec, s[2:3]
	s_waitcnt lgkmcnt(0)
	s_barrier

; __device__ __forceinline__ unsigned xb_ld(unsigned* p)              { return __hip_atomic_load(p, __ATOMIC_RELAXED, __HIP_MEMORY_SCOPE_AGENT); }
; __device__ __forceinline__ unsigned xb_add(unsigned* p, unsigned v) { return __hip_atomic_fetch_add(p, v, __ATOMIC_RELAXED, __HIP_MEMORY_SCOPE_AGENT); }
; #define XB_SPIN(cond, bar) do { unsigned _sp = 0; while (cond) { __builtin_amdgcn_s_sleep(1); \
;     if ((++_sp & 255u) == 0u) { if (xb_ld(&(bar)[XB_TMO])) break; if (_sp > XB_SPIN_CAP) { atomicAdd(&(bar)[XB_TMO], 1u); break; } } } } while (0)
; template <bool FLUSH> __device__ __forceinline__ void xcd_barrier(const XcdBarrier& b) {
;     ...
;             __builtin_amdgcn_fence(__ATOMIC_ACQUIRE, "agent");
;             xb_add(&bar[XB_XGEN(b.x)], 1u);
;             asm volatile("s_waitcnt vmcnt(0)" ::: "memory");
;         } else {
;             XB_SPIN(xb_ld(&bar[XB_XGEN(b.x)]) == gen, bar);
;             __builtin_amdgcn_fence(__ATOMIC_ACQUIRE, "agent");
;             asm volatile("s_waitcnt vmcnt(0)" ::: "memory");
;         }
;     }
;     __syncthreads();
.LBB0_1772:
	s_or_b64 exec, exec, s[6:7]
	v_mov_b32_e32 v0, 0x2000
	v_mov_b32_e32 v1, 1
	s_waitcnt vmcnt(0)
.LBB0_1773:
	s_or_b64 exec, exec, s[2:3]
	s_waitcnt lgkmcnt(0)
	s_barrier

; __device__ __forceinline__ unsigned xb_ld(unsigned* p)              { return __hip_atomic_load(p, __ATOMIC_RELAXED, __HIP_MEMORY_SCOPE_AGENT); }
; __device__ __forceinline__ unsigned xb_add(unsigned* p, unsigned v) { return __hip_atomic_fetch_add(p, v, __ATOMIC_RELAXED, __HIP_MEMORY_SCOPE_AGENT); }
; #define XB_SPIN(cond, bar) do { unsigned _sp = 0; while (cond) { __builtin_amdgcn_s_sleep(1); \
;     if ((++_sp & 255u) == 0u) { if (xb_ld(&(bar)[XB_TMO])) break; if (_sp > XB_SPIN_CAP) { atomicAdd(&(bar)[XB_TMO], 1u); break; } } } } while (0)
; template <bool FLUSH> __device__ __forceinline__ void xcd_barrier(const XcdBarrier& b) {
;     ...
;             __builtin_amdgcn_fence(__ATOMIC_ACQUIRE, "agent");
;             xb_add(&bar[XB_XGEN(b.x)], 1u);
;             asm volatile("s_waitcnt vmcnt(0)" ::: "memory");
;         } else {
;             XB_SPIN(xb_ld(&bar[XB_XGEN(b.x)]) == gen, bar);
;             __builtin_amdgcn_fence(__ATOMIC_ACQUIRE, "agent");
;             asm volatile("s_waitcnt vmcnt(0)" ::: "memory");
;         }
;     }
;     __syncthreads();
.LBB0_1986:
	s_or_b64 exec, exec, s[6:7]
	v_mov_b32_e32 v0, 0x2000
	v_mov_b32_e32 v1, 1
	s_waitcnt vmcnt(0)
.LBB0_1987:
	s_or_b64 exec, exec, s[2:3]
	s_waitcnt lgkmcnt(0)
	s_barrier

; __device__ __forceinline__ unsigned xb_ld(unsigned* p)              { return __hip_atomic_load(p, __ATOMIC_RELAXED, __HIP_MEMORY_SCOPE_AGENT); }
; __device__ __forceinline__ unsigned xb_add(unsigned* p, unsigned v) { return __hip_atomic_fetch_add(p, v, __ATOMIC_RELAXED, __HIP_MEMORY_SCOPE_AGENT); }
; #define XB_SPIN(cond, bar) do { unsigned _sp = 0; while (cond) { __builtin_amdgcn_s_sleep(1); \
;     if ((++_sp & 255u) == 0u) { if (xb_ld(&(bar)[XB_TMO])) break; if (_sp > XB_SPIN_CAP) { atomicAdd(&(bar)[XB_TMO], 1u); break; } } } } while (0)
; template <bool FLUSH> __device__ __forceinline__ void xcd_barrier(const XcdBarrier& b) {
;     ...
;             __builtin_amdgcn_fence(__ATOMIC_ACQUIRE, "agent");
;             xb_add(&bar[XB_XGEN(b.x)], 1u);
;             asm volatile("s_waitcnt vmcnt(0)" ::: "memory");
;         } else {
;             XB_SPIN(xb_ld(&bar[XB_XGEN(b.x)]) == gen, bar);
;             __builtin_amdgcn_fence(__ATOMIC_ACQUIRE, "agent");
;             asm volatile("s_waitcnt vmcnt(0)" ::: "memory");
;         }
;     }
;     __syncthreads();
.LBB0_2080:
	s_or_b64 exec, exec, s[6:7]
	v_mov_b32_e32 v0, 0x2000
	v_mov_b32_e32 v1, 1
	s_waitcnt vmcnt(0)
.LBB0_2081:
	s_or_b64 exec, exec, s[2:3]
	s_waitcnt lgkmcnt(0)
	s_barrier

; __device__ __forceinline__ unsigned xb_ld(unsigned* p)              { return __hip_atomic_load(p, __ATOMIC_RELAXED, __HIP_MEMORY_SCOPE_AGENT); }
; __device__ __forceinline__ unsigned xb_add(unsigned* p, unsigned v) { return __hip_atomic_fetch_add(p, v, __ATOMIC_RELAXED, __HIP_MEMORY_SCOPE_AGENT); }
; #define XB_SPIN(cond, bar) do { unsigned _sp = 0; while (cond) { __builtin_amdgcn_s_sleep(1); \
;     if ((++_sp & 255u) == 0u) { if (xb_ld(&(bar)[XB_TMO])) break; if (_sp > XB_SPIN_CAP) { atomicAdd(&(bar)[XB_TMO], 1u); break; } } } } while (0)
; template <bool FLUSH> __device__ __forceinline__ void xcd_barrier(const XcdBarrier& b) {
;     ...
;             __builtin_amdgcn_fence(__ATOMIC_ACQUIRE, "agent");
;             xb_add(&bar[XB_XGEN(b.x)], 1u);
;             asm volatile("s_waitcnt vmcnt(0)" ::: "memory");
;         } else {
;             XB_SPIN(xb_ld(&bar[XB_XGEN(b.x)]) == gen, bar);
;             __builtin_amdgcn_fence(__ATOMIC_ACQUIRE, "agent");
;             asm volatile("s_waitcnt vmcnt(0)" ::: "memory");
;         }
;     }
;     __syncthreads();
.LBB0_2172:
	s_or_b64 exec, exec, s[6:7]
	v_mov_b32_e32 v0, 0x2000
	v_mov_b32_e32 v1, 1
	s_waitcnt vmcnt(0)
.LBB0_2173:
	s_or_b64 exec, exec, s[2:3]
	s_waitcnt lgkmcnt(0)
	s_barrier

; __device__ __forceinline__ unsigned xb_ld(unsigned* p)              { return __hip_atomic_load(p, __ATOMIC_RELAXED, __HIP_MEMORY_SCOPE_AGENT); }
; __device__ __forceinline__ unsigned xb_add(unsigned* p, unsigned v) { return __hip_atomic_fetch_add(p, v, __ATOMIC_RELAXED, __HIP_MEMORY_SCOPE_AGENT); }
; #define XB_SPIN(cond, bar) do { unsigned _sp = 0; while (cond) { __builtin_amdgcn_s_sleep(1); \
;     if ((++_sp & 255u) == 0u) { if (xb_ld(&(bar)[XB_TMO])) break; if (_sp > XB_SPIN_CAP) { atomicAdd(&(bar)[XB_TMO], 1u); break; } } } } while (0)
; template <bool FLUSH> __device__ __forceinline__ void xcd_barrier(const XcdBarrier& b) {
;     ...
;             __builtin_amdgcn_fence(__ATOMIC_ACQUIRE, "agent");
;             xb_add(&bar[XB_XGEN(b.x)], 1u);
;             asm volatile("s_waitcnt vmcnt(0)" ::: "memory");
;         } else {
;             XB_SPIN(xb_ld(&bar[XB_XGEN(b.x)]) == gen, bar);
;             __builtin_amdgcn_fence(__ATOMIC_ACQUIRE, "agent");
;             asm volatile("s_waitcnt vmcnt(0)" ::: "memory");
;         }
;     }
;     __syncthreads();
.LBB0_2227:
	s_or_b64 exec, exec, s[4:5]
	v_mov_b32_e32 v0, 0x2000
	v_mov_b32_e32 v1, 1
	s_waitcnt vmcnt(0)
.LBB0_2228:
	s_or_b64 exec, exec, s[0:1]
	s_waitcnt lgkmcnt(0)
	s_barrier
